# stacked: conv loop rewrite, final-norm + phase-0 norm loops (gains hoisted, next row prefetched), HGRN scan double-buffered, LRU chunk-aggregate loads batched
# baseline (speedup 1.0000x reference)
; __device__ __forceinline__ void norm_rows_bf16(const float* X, const float* gain, bf16_t* O, int gw, int NGW, int lane) {
;     for (int m = gw; m < NTOK; m += NGW) {
;         const f32x4* xr = (const f32x4*)(X + (size_t)m * DM) + lane;
;         f32x4 v[8]; float s = 0.f;
; #pragma unroll
;         for (int j = 0; j < 8; ++j) { v[j] = __builtin_nontemporal_load(xr + 64 * j); s += (v[j].x * v[j].x + v[j].y * v[j].y) + (v[j].z * v[j].z + v[j].w * v[j].w); }
.LBB0_44:
	s_cmpk_gt_i32 s54, 0x3fff
	s_cbranch_scc1 .LBB0_48
	v_mbcnt_lo_u32_b32 v0, -1, 0
	v_mbcnt_hi_u32_b32 v0, -1, v0
	v_and_b32_e32 v1, 64, v0
	v_add_u32_e32 v1, 64, v1
	v_xor_b32_e32 v2, 1, v0
	v_cmp_lt_i32_e32 vcc, v2, v1
	v_ashrrev_i32_e32 v21, 31, v20
	s_mov_b64 s[4:5], 0x1400
	v_cndmask_b32_e32 v2, v0, v2, vcc
	v_lshlrev_b32_e32 v36, 2, v2
	v_xor_b32_e32 v2, 2, v0
	v_cmp_lt_i32_e32 vcc, v2, v1
	s_ashr_i32 s55, s54, 31
	s_mov_b32 s9, s93
	v_cndmask_b32_e32 v2, v0, v2, vcc
	v_lshlrev_b32_e32 v37, 2, v2
	v_xor_b32_e32 v2, 4, v0
	v_cmp_lt_i32_e32 vcc, v2, v1
	s_mov_b64 s[0:1], 0x1000
	s_mov_b32 s3, 0xf800000
	v_cndmask_b32_e32 v2, v0, v2, vcc
	v_lshlrev_b32_e32 v38, 2, v2
	v_xor_b32_e32 v2, 8, v0
	v_cmp_lt_i32_e32 vcc, v2, v1
	v_mov_b32_e32 v42, 0x260
	s_mov_b32 s8, s54
	v_cndmask_b32_e32 v2, v0, v2, vcc
	v_lshlrev_b32_e32 v39, 2, v2
	v_xor_b32_e32 v2, 16, v0
	v_cmp_lt_i32_e32 vcc, v2, v1
	s_nop 1
	v_cndmask_b32_e32 v2, v0, v2, vcc
	v_lshlrev_b32_e32 v40, 2, v2
	v_xor_b32_e32 v2, 32, v0
	v_cmp_lt_i32_e32 vcc, v2, v1
	s_nop 1
	v_cndmask_b32_e32 v0, v0, v2, vcc
	v_lshlrev_b32_e32 v41, 2, v0
	v_lshlrev_b64 v[0:1], 4, v[20:21]
	v_lshl_add_u64 v[22:23], s[60:61], 0, v[0:1]
	v_lshl_add_u64 v[26:27], v[22:23], 0, s[4:5]
	s_mov_b64 s[4:5], 0x1800
	v_lshl_add_u64 v[28:29], v[22:23], 0, s[4:5]
	s_mov_b64 s[4:5], 0x1c00
	v_lshl_add_u64 v[30:31], v[22:23], 0, s[4:5]
	s_lshl_b64 s[4:5], s[54:55], 13
	s_add_u32 s4, s56, s4
	s_addc_u32 s5, s57, s5
	v_lshl_add_u64 v[0:1], s[4:5], 0, v[0:1]
	s_ashr_i32 s93, s92, 31
	v_lshl_add_u64 v[24:25], v[22:23], 0, s[0:1]
	v_lshl_add_u64 v[32:33], v[0:1], 0, s[0:1]
	s_lshl_b64 s[4:5], s[92:93], 13
	s_lshl_b64 s[0:1], s[54:55], 12
	s_add_u32 s0, s90, s0
	s_addc_u32 s1, s91, s1
	v_lshl_add_u64 v[0:1], v[20:21], 3, s[0:1]
	s_mov_b64 s[0:1], 0x6800000
	v_lshl_add_u64 v[34:35], v[0:1], 0, s[0:1]
	s_lshl_b64 s[6:7], s[92:93], 12
	v_mov_b32_e32 v21, 0x358637bd
	global_load_dwordx4 v[96:99], v[22:23], off
	global_load_dwordx4 v[100:103], v[22:23], off offset:1024
	global_load_dwordx4 v[104:107], v[22:23], off offset:2048
	global_load_dwordx4 v[108:111], v[22:23], off offset:3072
	global_load_dwordx4 v[112:115], v[24:25], off
	global_load_dwordx4 v[116:119], v[26:27], off
	global_load_dwordx4 v[120:123], v[28:29], off
	global_load_dwordx4 v[124:127], v[30:31], off
	global_load_dwordx4 v[128:131], v[32:33], off offset:-4096 nt
	global_load_dwordx4 v[132:135], v[32:33], off offset:-3072 nt
	global_load_dwordx4 v[136:139], v[32:33], off offset:-2048 nt
	global_load_dwordx4 v[140:143], v[32:33], off offset:-1024 nt
	global_load_dwordx4 v[144:147], v[32:33], off nt
	global_load_dwordx4 v[148:151], v[32:33], off offset:1024 nt
	global_load_dwordx4 v[152:155], v[32:33], off offset:2048 nt
	global_load_dwordx4 v[156:159], v[32:33], off offset:3072 nt
	s_waitcnt vmcnt(0)
	s_branch .Ln0_enter

; __device__ __forceinline__ void norm_rows_bf16(const float* X, const float* gain, bf16_t* O, int gw, int NGW, int lane) {
;     for (int m = gw; m < NTOK; m += NGW) {
;         const f32x4* xr = (const f32x4*)(X + (size_t)m * DM) + lane;
;         f32x4 v[8]; float s = 0.f;
; #pragma unroll
;         for (int j = 0; j < 8; ++j) { v[j] = __builtin_nontemporal_load(xr + 64 * j); s += (v[j].x * v[j].x + v[j].y * v[j].y) + (v[j].z * v[j].z + v[j].w * v[j].w); }
;         const float rstd = 1.0f / sqrtf(wave_sum(s) * (1.0f / DM) + 1e-6f);
.Ln0_enter:
	v_mov_b64_e32 v[44:45], v[128:129]
	v_mov_b64_e32 v[46:47], v[130:131]
	v_mov_b64_e32 v[8:9], v[132:133]
	v_mov_b64_e32 v[10:11], v[134:135]
	v_mov_b64_e32 v[48:49], v[136:137]
	v_mov_b64_e32 v[50:51], v[138:139]
	v_mov_b64_e32 v[52:53], v[140:141]
	v_mov_b64_e32 v[54:55], v[142:143]
	v_mov_b64_e32 v[4:5], v[144:145]
	v_mov_b64_e32 v[6:7], v[146:147]
	v_mov_b64_e32 v[16:17], v[148:149]
	v_mov_b64_e32 v[18:19], v[150:151]
	v_mov_b64_e32 v[12:13], v[152:153]
	v_mov_b64_e32 v[14:15], v[154:155]
	v_mov_b64_e32 v[0:1], v[156:157]
	v_mov_b64_e32 v[2:3], v[158:159]
	s_add_i32 s8, s8, s92
	s_cmpk_lt_i32 s8, 0x4000
	s_cselect_b32 s98, s4, 0
	s_cselect_b32 s99, s5, 0
	v_lshl_add_u64 v[32:33], v[32:33], 0, s[98:99]
	global_load_dwordx4 v[128:131], v[32:33], off offset:-4096 nt
	global_load_dwordx4 v[132:135], v[32:33], off offset:-3072 nt
	global_load_dwordx4 v[136:139], v[32:33], off offset:-2048 nt
	global_load_dwordx4 v[140:143], v[32:33], off offset:-1024 nt
	global_load_dwordx4 v[144:147], v[32:33], off nt
	global_load_dwordx4 v[148:151], v[32:33], off offset:1024 nt
	global_load_dwordx4 v[152:155], v[32:33], off offset:2048 nt
	global_load_dwordx4 v[156:159], v[32:33], off offset:3072 nt
	v_mov_b32_e32 v62, v45
	v_mov_b32_e32 v63, v9
	v_mov_b32_e32 v66, v47
	v_mov_b32_e32 v67, v11
	v_mov_b32_e32 v60, v44
	v_mov_b32_e32 v61, v8
	v_mov_b32_e32 v64, v46
	v_mov_b32_e32 v65, v10
	v_pk_mul_f32 v[68:69], v[50:51], v[50:51]
	v_pk_mul_f32 v[70:71], v[48:49], v[48:49]
	v_pk_mul_f32 v[62:63], v[62:63], v[62:63]
	v_pk_mul_f32 v[66:67], v[66:67], v[66:67]
	v_pk_mov_b32 v[84:85], v[70:71], v[68:69] op_sel:[1,0]
	v_mov_b32_e32 v71, v69
	v_pk_fma_f32 v[60:61], v[60:61], v[60:61], v[62:63]
	v_pk_fma_f32 v[62:63], v[64:65], v[64:65], v[66:67]
	v_mul_f32_e32 v72, v53, v53
	v_mul_f32_e32 v74, v55, v55
	v_pk_add_f32 v[64:65], v[84:85], v[70:71]
	v_pk_add_f32 v[60:61], v[60:61], v[62:63]
	v_mul_f32_e32 v43, v4, v4
	v_mul_f32_e32 v83, v5, v5
	v_mul_f32_e32 v86, v6, v6
	v_mul_f32_e32 v87, v7, v7
	v_pk_fma_f32 v[68:69], v[52:53], v[52:53], v[72:73] op_sel_hi:[1,1,0]
	v_pk_fma_f32 v[72:73], v[54:55], v[54:55], v[74:75] op_sel_hi:[1,1,0]
	v_pk_add_f32 v[62:63], v[64:65], v[64:65] op_sel:[0,1] op_sel_hi:[1,0]
	v_pk_add_f32 v[60:61], v[60:61], v[60:61] op_sel:[0,1] op_sel_hi:[1,0]
	v_pk_mul_f32 v[76:77], v[18:19], v[18:19]
	v_pk_mul_f32 v[78:79], v[16:17], v[16:17]
	v_mov_b32_e32 v69, v86
	v_mov_b32_e32 v73, v87
	v_mov_b32_e32 v63, v83
	v_mov_b32_e32 v61, v43
	v_pk_mov_b32 v[74:75], v[78:79], v[76:77] op_sel:[1,0]
	v_mov_b32_e32 v79, v77
	v_pk_add_f32 v[64:65], v[68:69], v[72:73]
	v_pk_add_f32 v[60:61], v[60:61], v[62:63]
	v_mul_f32_e32 v80, v13, v13
	v_mul_f32_e32 v82, v15, v15
	v_pk_add_f32 v[66:67], v[74:75], v[78:79]
	v_pk_add_f32 v[60:61], v[60:61], v[64:65]
	v_mul_f32_e32 v88, v0, v0
	v_mul_f32_e32 v89, v1, v1
	v_mul_f32_e32 v90, v2, v2
	v_mul_f32_e32 v91, v3, v3
	v_pk_fma_f32 v[76:77], v[12:13], v[12:13], v[80:81] op_sel_hi:[1,1,0]
	v_pk_fma_f32 v[80:81], v[14:15], v[14:15], v[82:83] op_sel_hi:[1,1,0]
	v_pk_add_f32 v[66:67], v[66:67], v[66:67] op_sel:[0,1] op_sel_hi:[1,0]
	v_pk_add_f32 v[60:61], v[60:61], v[60:61] op_sel:[0,1] op_sel_hi:[1,0]
	v_mov_b32_e32 v77, v90
	v_mov_b32_e32 v81, v91
	v_mov_b32_e32 v67, v89
	v_mov_b32_e32 v61, v88
	v_pk_add_f32 v[68:69], v[76:77], v[80:81]
	v_pk_add_f32 v[60:61], v[60:61], v[66:67]
	s_nop 0
	v_pk_add_f32 v[60:61], v[60:61], v[68:69]
	s_nop 0
	v_add_f32_e32 v43, v60, v61
	ds_bpermute_b32 v60, v36, v43
	s_waitcnt lgkmcnt(0)
	v_add_f32_e32 v43, v43, v60
	ds_bpermute_b32 v60, v37, v43
	s_waitcnt lgkmcnt(0)
	v_add_f32_e32 v43, v43, v60
	ds_bpermute_b32 v60, v38, v43
	s_waitcnt lgkmcnt(0)
	v_add_f32_e32 v43, v43, v60
	ds_bpermute_b32 v60, v39, v43
	s_waitcnt lgkmcnt(0)
; __device__ __forceinline__ void norm_rows_bf16(const float* X, const float* gain, bf16_t* O, int gw, int NGW, int lane) {
;     ...
;         const float rstd = 1.0f / sqrtf(wave_sum(s) * (1.0f / DM) + 1e-6f);
;         u32x2* o8 = (u32x2*)(O + (size_t)m * DM) + lane;
; #pragma unroll
;         for (int j = 0; j < 8; ++j) { const f32x4 g = ((const f32x4*)gain)[lane + 64 * j]; u32x2 w; w.x = pk2(v[j].x * rstd * g.x, v[j].y * rstd * g.y); w.y = pk2(v[j].z * rstd * g.z, v[j].w * rstd * g.w); o8[64 * j] = w; }
	v_add_f32_e32 v43, v43, v60
	ds_bpermute_b32 v60, v40, v43
	s_waitcnt lgkmcnt(0)
	v_add_f32_e32 v43, v43, v60
	ds_bpermute_b32 v60, v41, v43
	s_waitcnt lgkmcnt(0)
	v_add_f32_e32 v43, v43, v60
	v_fmamk_f32 v43, v43, 0x3a000000, v21
	v_mul_f32_e32 v60, 0x4f800000, v43
	v_cmp_gt_f32_e32 vcc, s3, v43
	s_nop 1
	v_cndmask_b32_e32 v43, v43, v60, vcc
	v_sqrt_f32_e32 v60, v43
	s_nop 0
	v_add_u32_e32 v61, -1, v60
	v_add_u32_e32 v62, 1, v60
	v_fma_f32 v63, -v61, v60, v43
	v_fma_f32 v64, -v62, v60, v43
	v_cmp_ge_f32_e64 s[0:1], 0, v63
	s_nop 1
	v_cndmask_b32_e64 v60, v60, v61, s[0:1]
	v_cmp_lt_f32_e64 s[0:1], 0, v64
	s_nop 1
	v_cndmask_b32_e64 v60, v60, v62, s[0:1]
	v_mul_f32_e32 v61, 0x37800000, v60
	v_cndmask_b32_e32 v60, v60, v61, vcc
	v_cmp_class_f32_e32 vcc, v43, v42
	s_nop 1
	v_cndmask_b32_e32 v43, v60, v43, vcc
	v_div_scale_f32 v60, s[0:1], v43, v43, 1.0
	v_rcp_f32_e32 v62, v60
	v_div_scale_f32 v61, vcc, 1.0, v43, 1.0
	v_fma_f32 v63, -v60, v62, 1.0
	v_fmac_f32_e32 v62, v63, v62
	v_mul_f32_e32 v63, v61, v62
	v_fma_f32 v64, -v60, v63, v61
	v_fmac_f32_e32 v63, v64, v62
	v_fma_f32 v60, -v60, v63, v61
	v_div_fmas_f32 v60, v60, v62, v63
	v_div_fixup_f32 v60, v60, v43, 1.0
	v_pk_mul_f32 v[44:45], v[44:45], v[60:61] op_sel_hi:[1,0]
	v_pk_mul_f32 v[46:47], v[46:47], v[60:61] op_sel_hi:[1,0]
	v_pk_mul_f32 v[44:45], v[96:97], v[44:45]
	v_pk_mul_f32 v[46:47], v[98:99], v[46:47]
	v_cvt_pk_bf16_f32 v44, v44, v45
	v_cvt_pk_bf16_f32 v45, v46, v47
	global_store_dwordx2 v[34:35], v[44:45], off
	v_pk_mul_f32 v[8:9], v[8:9], v[60:61] op_sel_hi:[1,0]
	v_pk_mul_f32 v[10:11], v[10:11], v[60:61] op_sel_hi:[1,0]
	v_pk_mul_f32 v[4:5], v[4:5], v[60:61] op_sel_hi:[1,0]
	v_pk_mul_f32 v[6:7], v[6:7], v[60:61] op_sel_hi:[1,0]
	v_pk_mul_f32 v[0:1], v[0:1], v[60:61] op_sel_hi:[1,0]
	v_pk_mul_f32 v[2:3], v[2:3], v[60:61] op_sel_hi:[1,0]
	v_pk_mul_f32 v[8:9], v[100:101], v[8:9]
	v_pk_mul_f32 v[10:11], v[102:103], v[10:11]
	v_cvt_pk_bf16_f32 v8, v8, v9
	v_cvt_pk_bf16_f32 v9, v10, v11
	global_store_dwordx2 v[34:35], v[8:9], off offset:512
	v_pk_mul_f32 v[44:45], v[48:49], v[60:61] op_sel_hi:[1,0]
	v_pk_mul_f32 v[46:47], v[50:51], v[60:61] op_sel_hi:[1,0]
	v_pk_mul_f32 v[8:9], v[104:105], v[44:45]
	v_pk_mul_f32 v[10:11], v[106:107], v[46:47]
	v_cvt_pk_bf16_f32 v8, v8, v9
	v_cvt_pk_bf16_f32 v9, v10, v11
	global_store_dwordx2 v[34:35], v[8:9], off offset:1024
	v_pk_mul_f32 v[44:45], v[52:53], v[60:61] op_sel_hi:[1,0]
	v_pk_mul_f32 v[46:47], v[54:55], v[60:61] op_sel_hi:[1,0]
	v_pk_mul_f32 v[8:9], v[108:109], v[44:45]
	v_pk_mul_f32 v[10:11], v[110:111], v[46:47]
	v_cvt_pk_bf16_f32 v8, v8, v9
	v_cvt_pk_bf16_f32 v9, v10, v11
	global_store_dwordx2 v[34:35], v[8:9], off offset:1536
	v_pk_mul_f32 v[4:5], v[4:5], v[112:113]
	v_pk_mul_f32 v[6:7], v[6:7], v[114:115]
	v_cvt_pk_bf16_f32 v4, v4, v5
	v_cvt_pk_bf16_f32 v5, v6, v7
	global_store_dwordx2 v[34:35], v[4:5], off offset:2048
	v_pk_mul_f32 v[8:9], v[16:17], v[60:61] op_sel_hi:[1,0]
	v_pk_mul_f32 v[10:11], v[18:19], v[60:61] op_sel_hi:[1,0]
	v_pk_mul_f32 v[4:5], v[8:9], v[116:117]
	v_pk_mul_f32 v[6:7], v[10:11], v[118:119]
	v_cvt_pk_bf16_f32 v4, v4, v5
	v_cvt_pk_bf16_f32 v5, v6, v7
	global_store_dwordx2 v[34:35], v[4:5], off offset:2560
	v_pk_mul_f32 v[8:9], v[12:13], v[60:61] op_sel_hi:[1,0]
	v_pk_mul_f32 v[10:11], v[14:15], v[60:61] op_sel_hi:[1,0]
	v_pk_mul_f32 v[4:5], v[8:9], v[120:121]
	v_pk_mul_f32 v[6:7], v[10:11], v[122:123]
	v_cvt_pk_bf16_f32 v4, v4, v5
	v_cvt_pk_bf16_f32 v5, v6, v7
	global_store_dwordx2 v[34:35], v[4:5], off offset:3072
	v_pk_mul_f32 v[0:1], v[0:1], v[124:125]
	v_pk_mul_f32 v[2:3], v[2:3], v[126:127]
	v_cvt_pk_bf16_f32 v0, v0, v1
	v_cvt_pk_bf16_f32 v1, v2, v3
	global_store_dwordx2 v[34:35], v[0:1], off offset:3584
	v_lshl_add_u64 v[34:35], v[34:35], 0, s[6:7]
	s_cbranch_scc1 .LBB0_46
	s_mov_b32 s93, s9

; __device__ __forceinline__ float bflo(unsigned w) { return __uint_as_float(w << 16); }
; __device__ __forceinline__ float bfhi(unsigned w) { return __uint_as_float(w & 0xffff0000u); }
; __global__ void __launch_bounds__(512, 2) mega(Params p, int ph_lo, int ph_hi) {
;     ...
;             for (int i = 0; S.next(i, uu); ++i) {
;                 const int ch = uu.z * 256 + uu.pn * 128 + chl, cidx = 2 * uu.pm + half;
;                 const unsigned* src = LAU + ((size_t)cidx * 128 + 64 * sub) * 1024 + ch;
;                 float P = 1.f, H = 0.f;
; #pragma unroll 16
;                 for (int t = 0; t < 64; ++t) { const unsigned w = src[(size_t)t * 1024]; const float a = __expf(bflo(w)); H = a * H + bfhi(w); P *= a; }
.LBB0_391:
	s_mov_b64 s[6:7], 0x1000
	v_add_co_u32_e32 v14, vcc, 0x16800000, v10
	s_nop 1
	v_addc_co_u32_e32 v15, vcc, 0, v11, vcc
	global_load_dword v47, v[14:15], off
	v_lshl_add_u64 v[14:15], v[14:15], 0, s[6:7]
	global_load_dword v48, v[14:15], off
	v_lshl_add_u64 v[14:15], v[14:15], 0, s[6:7]
	global_load_dword v49, v[14:15], off
	v_lshl_add_u64 v[14:15], v[14:15], 0, s[6:7]
	global_load_dword v50, v[14:15], off
	v_lshl_add_u64 v[14:15], v[14:15], 0, s[6:7]
	global_load_dword v51, v[14:15], off
	v_lshl_add_u64 v[14:15], v[14:15], 0, s[6:7]
	global_load_dword v52, v[14:15], off
	v_lshl_add_u64 v[14:15], v[14:15], 0, s[6:7]
	global_load_dword v53, v[14:15], off
	v_lshl_add_u64 v[14:15], v[14:15], 0, s[6:7]
	global_load_dword v54, v[14:15], off
	v_lshl_add_u64 v[14:15], v[14:15], 0, s[6:7]
	global_load_dword v55, v[14:15], off
	v_lshl_add_u64 v[14:15], v[14:15], 0, s[6:7]
	global_load_dword v56, v[14:15], off
	v_lshl_add_u64 v[14:15], v[14:15], 0, s[6:7]
	global_load_dword v57, v[14:15], off
	v_lshl_add_u64 v[14:15], v[14:15], 0, s[6:7]
	global_load_dword v58, v[14:15], off
	v_lshl_add_u64 v[14:15], v[14:15], 0, s[6:7]
	global_load_dword v59, v[14:15], off
	v_lshl_add_u64 v[14:15], v[14:15], 0, s[6:7]
	global_load_dword v60, v[14:15], off
	v_lshl_add_u64 v[14:15], v[14:15], 0, s[6:7]
	global_load_dword v61, v[14:15], off
	v_lshl_add_u64 v[14:15], v[14:15], 0, s[6:7]
	global_load_dword v62, v[14:15], off
	v_lshl_add_u64 v[14:15], v[14:15], 0, s[6:7]
	global_load_dword v63, v[14:15], off
	v_lshl_add_u64 v[14:15], v[14:15], 0, s[6:7]
	global_load_dword v64, v[14:15], off
	v_lshl_add_u64 v[14:15], v[14:15], 0, s[6:7]
	global_load_dword v65, v[14:15], off
	v_lshl_add_u64 v[14:15], v[14:15], 0, s[6:7]
	global_load_dword v66, v[14:15], off
	v_lshl_add_u64 v[14:15], v[14:15], 0, s[6:7]
	global_load_dword v67, v[14:15], off
	v_lshl_add_u64 v[14:15], v[14:15], 0, s[6:7]
	global_load_dword v68, v[14:15], off
	v_lshl_add_u64 v[14:15], v[14:15], 0, s[6:7]
	global_load_dword v69, v[14:15], off
	v_lshl_add_u64 v[14:15], v[14:15], 0, s[6:7]
	global_load_dword v70, v[14:15], off
	v_lshl_add_u64 v[14:15], v[14:15], 0, s[6:7]
	global_load_dword v71, v[14:15], off
	v_lshl_add_u64 v[14:15], v[14:15], 0, s[6:7]
	global_load_dword v72, v[14:15], off
	v_lshl_add_u64 v[14:15], v[14:15], 0, s[6:7]
	global_load_dword v73, v[14:15], off
	v_lshl_add_u64 v[14:15], v[14:15], 0, s[6:7]
	global_load_dword v74, v[14:15], off
	v_lshl_add_u64 v[14:15], v[14:15], 0, s[6:7]
	global_load_dword v75, v[14:15], off
	v_lshl_add_u64 v[14:15], v[14:15], 0, s[6:7]
	global_load_dword v76, v[14:15], off
	v_lshl_add_u64 v[14:15], v[14:15], 0, s[6:7]
	global_load_dword v77, v[14:15], off
	v_lshl_add_u64 v[14:15], v[14:15], 0, s[6:7]
	global_load_dword v78, v[14:15], off
	v_lshl_add_u64 v[14:15], v[14:15], 0, s[6:7]
	global_load_dword v79, v[14:15], off
	v_lshl_add_u64 v[14:15], v[14:15], 0, s[6:7]
	global_load_dword v80, v[14:15], off
	v_lshl_add_u64 v[14:15], v[14:15], 0, s[6:7]
	global_load_dword v81, v[14:15], off
	v_lshl_add_u64 v[14:15], v[14:15], 0, s[6:7]
	global_load_dword v82, v[14:15], off
	v_lshl_add_u64 v[14:15], v[14:15], 0, s[6:7]
	global_load_dword v83, v[14:15], off
	v_lshl_add_u64 v[14:15], v[14:15], 0, s[6:7]
	global_load_dword v84, v[14:15], off
	v_lshl_add_u64 v[14:15], v[14:15], 0, s[6:7]
	global_load_dword v85, v[14:15], off
	v_lshl_add_u64 v[14:15], v[14:15], 0, s[6:7]
	global_load_dword v86, v[14:15], off
	v_lshl_add_u64 v[14:15], v[14:15], 0, s[6:7]
	global_load_dword v87, v[14:15], off
	v_lshl_add_u64 v[14:15], v[14:15], 0, s[6:7]
	global_load_dword v88, v[14:15], off
	v_lshl_add_u64 v[14:15], v[14:15], 0, s[6:7]
	global_load_dword v89, v[14:15], off
	v_lshl_add_u64 v[14:15], v[14:15], 0, s[6:7]
	global_load_dword v90, v[14:15], off
	v_lshl_add_u64 v[14:15], v[14:15], 0, s[6:7]
	global_load_dword v91, v[14:15], off
	v_lshl_add_u64 v[14:15], v[14:15], 0, s[6:7]
	global_load_dword v92, v[14:15], off
	v_lshl_add_u64 v[14:15], v[14:15], 0, s[6:7]
	global_load_dword v93, v[14:15], off
	v_lshl_add_u64 v[14:15], v[14:15], 0, s[6:7]
	global_load_dword v94, v[14:15], off
	v_lshl_add_u64 v[14:15], v[14:15], 0, s[6:7]
	global_load_dword v95, v[14:15], off
	v_lshl_add_u64 v[14:15], v[14:15], 0, s[6:7]
	global_load_dword v96, v[14:15], off
	v_lshl_add_u64 v[14:15], v[14:15], 0, s[6:7]
	global_load_dword v97, v[14:15], off
	v_lshl_add_u64 v[14:15], v[14:15], 0, s[6:7]
	global_load_dword v98, v[14:15], off
	v_lshl_add_u64 v[14:15], v[14:15], 0, s[6:7]
	global_load_dword v99, v[14:15], off
	v_lshl_add_u64 v[14:15], v[14:15], 0, s[6:7]
	global_load_dword v100, v[14:15], off
	v_lshl_add_u64 v[14:15], v[14:15], 0, s[6:7]
	global_load_dword v101, v[14:15], off
	v_lshl_add_u64 v[14:15], v[14:15], 0, s[6:7]
	global_load_dword v102, v[14:15], off
	v_lshl_add_u64 v[14:15], v[14:15], 0, s[6:7]
	global_load_dword v103, v[14:15], off
	v_lshl_add_u64 v[14:15], v[14:15], 0, s[6:7]
	global_load_dword v104, v[14:15], off
	v_lshl_add_u64 v[14:15], v[14:15], 0, s[6:7]
	global_load_dword v105, v[14:15], off
	v_lshl_add_u64 v[14:15], v[14:15], 0, s[6:7]
	global_load_dword v106, v[14:15], off
	v_lshl_add_u64 v[14:15], v[14:15], 0, s[6:7]
	global_load_dword v107, v[14:15], off
	v_lshl_add_u64 v[14:15], v[14:15], 0, s[6:7]
	global_load_dword v108, v[14:15], off
	v_lshl_add_u64 v[14:15], v[14:15], 0, s[6:7]
	global_load_dword v109, v[14:15], off
	v_lshl_add_u64 v[14:15], v[14:15], 0, s[6:7]
	global_load_dword v110, v[14:15], off
	s_waitcnt vmcnt(48)
; __device__ __forceinline__ float bflo(unsigned w) { return __uint_as_float(w << 16); }
; __device__ __forceinline__ float bfhi(unsigned w) { return __uint_as_float(w & 0xffff0000u); }
; __global__ void __launch_bounds__(512, 2) mega(Params p, int ph_lo, int ph_hi) {
;     ...
;                 float P = 1.f, H = 0.f;
; #pragma unroll 16
;                 for (int t = 0; t < 64; ++t) { const unsigned w = src[(size_t)t * 1024]; const float a = __expf(bflo(w)); H = a * H + bfhi(w); P *= a; }
	v_lshlrev_b32_e32 v20, 16, v47
	v_and_b32_e32 v47, 0xffff0000, v47
	v_mul_f32_e32 v20, 0x3fb8aa3b, v20
	v_lshlrev_b32_e32 v21, 16, v48
	v_and_b32_e32 v48, 0xffff0000, v48
	v_mul_f32_e32 v21, 0x3fb8aa3b, v21
	v_lshlrev_b32_e32 v22, 16, v49
	v_and_b32_e32 v49, 0xffff0000, v49
	v_mul_f32_e32 v22, 0x3fb8aa3b, v22
	v_lshlrev_b32_e32 v23, 16, v50
	v_and_b32_e32 v50, 0xffff0000, v50
	v_mul_f32_e32 v23, 0x3fb8aa3b, v23
	v_exp_f32_e32 v20, v20
	v_exp_f32_e32 v21, v21
	v_exp_f32_e32 v22, v22
	v_exp_f32_e32 v23, v23
	s_nop 0
	v_fmac_f32_e32 v47, v13, v20
	v_mul_f32_e32 v12, v12, v20
	v_fmac_f32_e32 v48, v47, v21
	v_mul_f32_e32 v12, v12, v21
	v_fmac_f32_e32 v49, v48, v22
	v_mul_f32_e32 v12, v12, v22
	v_fmac_f32_e32 v50, v49, v23
	v_mul_f32_e32 v12, v12, v23
	v_lshlrev_b32_e32 v20, 16, v51
	v_and_b32_e32 v51, 0xffff0000, v51
	v_mul_f32_e32 v20, 0x3fb8aa3b, v20
	v_lshlrev_b32_e32 v21, 16, v52
	v_and_b32_e32 v52, 0xffff0000, v52
	v_mul_f32_e32 v21, 0x3fb8aa3b, v21
	v_lshlrev_b32_e32 v22, 16, v53
	v_and_b32_e32 v53, 0xffff0000, v53
	v_mul_f32_e32 v22, 0x3fb8aa3b, v22
	v_lshlrev_b32_e32 v23, 16, v54
	v_and_b32_e32 v54, 0xffff0000, v54
	v_mul_f32_e32 v23, 0x3fb8aa3b, v23
	v_exp_f32_e32 v20, v20
	v_exp_f32_e32 v21, v21
	v_exp_f32_e32 v22, v22
	v_exp_f32_e32 v23, v23
	s_nop 0
	v_fmac_f32_e32 v51, v50, v20
	v_mul_f32_e32 v12, v12, v20
	v_fmac_f32_e32 v52, v51, v21
	v_mul_f32_e32 v12, v12, v21
	v_fmac_f32_e32 v53, v52, v22
	v_mul_f32_e32 v12, v12, v22
	v_fmac_f32_e32 v54, v53, v23
	v_mul_f32_e32 v12, v12, v23
	v_lshlrev_b32_e32 v20, 16, v55
	v_and_b32_e32 v55, 0xffff0000, v55
	v_mul_f32_e32 v20, 0x3fb8aa3b, v20
	v_lshlrev_b32_e32 v21, 16, v56
	v_and_b32_e32 v56, 0xffff0000, v56
	v_mul_f32_e32 v21, 0x3fb8aa3b, v21
	v_lshlrev_b32_e32 v22, 16, v57
	v_and_b32_e32 v57, 0xffff0000, v57
	v_mul_f32_e32 v22, 0x3fb8aa3b, v22
	v_lshlrev_b32_e32 v23, 16, v58
	v_and_b32_e32 v58, 0xffff0000, v58
	v_mul_f32_e32 v23, 0x3fb8aa3b, v23
	v_exp_f32_e32 v20, v20
	v_exp_f32_e32 v21, v21
	v_exp_f32_e32 v22, v22
	v_exp_f32_e32 v23, v23
	s_nop 0
	v_fmac_f32_e32 v55, v54, v20
	v_mul_f32_e32 v12, v12, v20
	v_fmac_f32_e32 v56, v55, v21
	v_mul_f32_e32 v12, v12, v21
	v_fmac_f32_e32 v57, v56, v22
	v_mul_f32_e32 v12, v12, v22
	v_fmac_f32_e32 v58, v57, v23
	v_mul_f32_e32 v12, v12, v23
	v_lshlrev_b32_e32 v20, 16, v59
	v_and_b32_e32 v59, 0xffff0000, v59
	v_mul_f32_e32 v20, 0x3fb8aa3b, v20
	v_lshlrev_b32_e32 v21, 16, v60
	v_and_b32_e32 v60, 0xffff0000, v60
	v_mul_f32_e32 v21, 0x3fb8aa3b, v21
	v_lshlrev_b32_e32 v22, 16, v61
	v_and_b32_e32 v61, 0xffff0000, v61
	v_mul_f32_e32 v22, 0x3fb8aa3b, v22
	v_lshlrev_b32_e32 v23, 16, v62
	v_and_b32_e32 v62, 0xffff0000, v62
	v_mul_f32_e32 v23, 0x3fb8aa3b, v23
	v_exp_f32_e32 v20, v20
	v_exp_f32_e32 v21, v21
	v_exp_f32_e32 v22, v22
	v_exp_f32_e32 v23, v23
	s_nop 0
	v_fmac_f32_e32 v59, v58, v20
	v_mul_f32_e32 v12, v12, v20
	v_fmac_f32_e32 v60, v59, v21
	v_mul_f32_e32 v12, v12, v21
	v_fmac_f32_e32 v61, v60, v22
	v_mul_f32_e32 v12, v12, v22
	v_fmac_f32_e32 v62, v61, v23
	v_mul_f32_e32 v12, v12, v23
	s_waitcnt vmcnt(32)
	v_lshlrev_b32_e32 v20, 16, v63
	v_and_b32_e32 v63, 0xffff0000, v63
	v_mul_f32_e32 v20, 0x3fb8aa3b, v20
	v_lshlrev_b32_e32 v21, 16, v64
	v_and_b32_e32 v64, 0xffff0000, v64
	v_mul_f32_e32 v21, 0x3fb8aa3b, v21
	v_lshlrev_b32_e32 v22, 16, v65
	v_and_b32_e32 v65, 0xffff0000, v65
	v_mul_f32_e32 v22, 0x3fb8aa3b, v22
	v_lshlrev_b32_e32 v23, 16, v66
	v_and_b32_e32 v66, 0xffff0000, v66
	v_mul_f32_e32 v23, 0x3fb8aa3b, v23
	v_exp_f32_e32 v20, v20
	v_exp_f32_e32 v21, v21
	v_exp_f32_e32 v22, v22
	v_exp_f32_e32 v23, v23
	s_nop 0
	v_fmac_f32_e32 v63, v62, v20
	v_mul_f32_e32 v12, v12, v20
	v_fmac_f32_e32 v64, v63, v21
	v_mul_f32_e32 v12, v12, v21
	v_fmac_f32_e32 v65, v64, v22
	v_mul_f32_e32 v12, v12, v22
	v_fmac_f32_e32 v66, v65, v23
	v_mul_f32_e32 v12, v12, v23
	v_lshlrev_b32_e32 v20, 16, v67
	v_and_b32_e32 v67, 0xffff0000, v67
	v_mul_f32_e32 v20, 0x3fb8aa3b, v20
	v_lshlrev_b32_e32 v21, 16, v68
	v_and_b32_e32 v68, 0xffff0000, v68
	v_mul_f32_e32 v21, 0x3fb8aa3b, v21
	v_lshlrev_b32_e32 v22, 16, v69
	v_and_b32_e32 v69, 0xffff0000, v69
	v_mul_f32_e32 v22, 0x3fb8aa3b, v22
	v_lshlrev_b32_e32 v23, 16, v70
	v_and_b32_e32 v70, 0xffff0000, v70
	v_mul_f32_e32 v23, 0x3fb8aa3b, v23
	v_exp_f32_e32 v20, v20
	v_exp_f32_e32 v21, v21
	v_exp_f32_e32 v22, v22
	v_exp_f32_e32 v23, v23
	s_nop 0
	v_fmac_f32_e32 v67, v66, v20
	v_mul_f32_e32 v12, v12, v20
	v_fmac_f32_e32 v68, v67, v21
	v_mul_f32_e32 v12, v12, v21
	v_fmac_f32_e32 v69, v68, v22
	v_mul_f32_e32 v12, v12, v22
	v_fmac_f32_e32 v70, v69, v23
	v_mul_f32_e32 v12, v12, v23
	v_lshlrev_b32_e32 v20, 16, v71
	v_and_b32_e32 v71, 0xffff0000, v71
	v_mul_f32_e32 v20, 0x3fb8aa3b, v20
	v_lshlrev_b32_e32 v21, 16, v72
	v_and_b32_e32 v72, 0xffff0000, v72
	v_mul_f32_e32 v21, 0x3fb8aa3b, v21
	v_lshlrev_b32_e32 v22, 16, v73
	v_and_b32_e32 v73, 0xffff0000, v73
	v_mul_f32_e32 v22, 0x3fb8aa3b, v22
	v_lshlrev_b32_e32 v23, 16, v74
	v_and_b32_e32 v74, 0xffff0000, v74
	v_mul_f32_e32 v23, 0x3fb8aa3b, v23
	v_exp_f32_e32 v20, v20
	v_exp_f32_e32 v21, v21
	v_exp_f32_e32 v22, v22
	v_exp_f32_e32 v23, v23
	s_nop 0
	v_fmac_f32_e32 v71, v70, v20
	v_mul_f32_e32 v12, v12, v20
	v_fmac_f32_e32 v72, v71, v21
	v_mul_f32_e32 v12, v12, v21
	v_fmac_f32_e32 v73, v72, v22
	v_mul_f32_e32 v12, v12, v22
	v_fmac_f32_e32 v74, v73, v23
	v_mul_f32_e32 v12, v12, v23
	v_lshlrev_b32_e32 v20, 16, v75
	v_and_b32_e32 v75, 0xffff0000, v75
	v_mul_f32_e32 v20, 0x3fb8aa3b, v20
	v_lshlrev_b32_e32 v21, 16, v76
	v_and_b32_e32 v76, 0xffff0000, v76
	v_mul_f32_e32 v21, 0x3fb8aa3b, v21
	v_lshlrev_b32_e32 v22, 16, v77
	v_and_b32_e32 v77, 0xffff0000, v77
	v_mul_f32_e32 v22, 0x3fb8aa3b, v22
	v_lshlrev_b32_e32 v23, 16, v78
	v_and_b32_e32 v78, 0xffff0000, v78
	v_mul_f32_e32 v23, 0x3fb8aa3b, v23
	v_exp_f32_e32 v20, v20
	v_exp_f32_e32 v21, v21
	v_exp_f32_e32 v22, v22
	v_exp_f32_e32 v23, v23
	s_nop 0
	v_fmac_f32_e32 v75, v74, v20
	v_mul_f32_e32 v12, v12, v20
	v_fmac_f32_e32 v76, v75, v21
	v_mul_f32_e32 v12, v12, v21
	v_fmac_f32_e32 v77, v76, v22
	v_mul_f32_e32 v12, v12, v22
	v_fmac_f32_e32 v78, v77, v23
	v_mul_f32_e32 v12, v12, v23
	s_waitcnt vmcnt(16)
; #define LAS __attribute__((address_space(3)))
; __device__ __forceinline__ float bflo(unsigned w) { return __uint_as_float(w << 16); }
; __device__ __forceinline__ float bfhi(unsigned w) { return __uint_as_float(w & 0xffff0000u); }
; __global__ void __launch_bounds__(512, 2) mega(Params p, int ph_lo, int ph_hi) {
;     ...
;                 for (int t = 0; t < 64; ++t) { const unsigned w = src[(size_t)t * 1024]; const float a = __expf(bflo(w)); H = a * H + bfhi(w); P *= a; }
;                 LAS float* X2 = (LAS float*)lds;
;                 if (sub == 1) { X2[(half * 128 + chl) * 2] = P; X2[(half * 128 + chl) * 2 + 1] = H; }
;                 __syncthreads();
;                 if (sub == 0) { const float P1 = X2[(half * 128 + chl) * 2], H1 = X2[(half * 128 + chl) * 2 + 1]; AGG[(size_t)cidx * 1024 + ch] = (f32x2){P * P1, P1 * H + H1}; }
;                 __syncthreads();
;             }
	v_lshlrev_b32_e32 v20, 16, v79
	v_and_b32_e32 v79, 0xffff0000, v79
	v_mul_f32_e32 v20, 0x3fb8aa3b, v20
	v_lshlrev_b32_e32 v21, 16, v80
	v_and_b32_e32 v80, 0xffff0000, v80
	v_mul_f32_e32 v21, 0x3fb8aa3b, v21
	v_lshlrev_b32_e32 v22, 16, v81
	v_and_b32_e32 v81, 0xffff0000, v81
	v_mul_f32_e32 v22, 0x3fb8aa3b, v22
	v_lshlrev_b32_e32 v23, 16, v82
	v_and_b32_e32 v82, 0xffff0000, v82
	v_mul_f32_e32 v23, 0x3fb8aa3b, v23
	v_exp_f32_e32 v20, v20
	v_exp_f32_e32 v21, v21
	v_exp_f32_e32 v22, v22
	v_exp_f32_e32 v23, v23
	s_nop 0
	v_fmac_f32_e32 v79, v78, v20
	v_mul_f32_e32 v12, v12, v20
	v_fmac_f32_e32 v80, v79, v21
	v_mul_f32_e32 v12, v12, v21
	v_fmac_f32_e32 v81, v80, v22
	v_mul_f32_e32 v12, v12, v22
	v_fmac_f32_e32 v82, v81, v23
	v_mul_f32_e32 v12, v12, v23
	v_lshlrev_b32_e32 v20, 16, v83
	v_and_b32_e32 v83, 0xffff0000, v83
	v_mul_f32_e32 v20, 0x3fb8aa3b, v20
	v_lshlrev_b32_e32 v21, 16, v84
	v_and_b32_e32 v84, 0xffff0000, v84
	v_mul_f32_e32 v21, 0x3fb8aa3b, v21
	v_lshlrev_b32_e32 v22, 16, v85
	v_and_b32_e32 v85, 0xffff0000, v85
	v_mul_f32_e32 v22, 0x3fb8aa3b, v22
	v_lshlrev_b32_e32 v23, 16, v86
	v_and_b32_e32 v86, 0xffff0000, v86
	v_mul_f32_e32 v23, 0x3fb8aa3b, v23
	v_exp_f32_e32 v20, v20
	v_exp_f32_e32 v21, v21
	v_exp_f32_e32 v22, v22
	v_exp_f32_e32 v23, v23
	s_nop 0
	v_fmac_f32_e32 v83, v82, v20
	v_mul_f32_e32 v12, v12, v20
	v_fmac_f32_e32 v84, v83, v21
	v_mul_f32_e32 v12, v12, v21
	v_fmac_f32_e32 v85, v84, v22
	v_mul_f32_e32 v12, v12, v22
	v_fmac_f32_e32 v86, v85, v23
	v_mul_f32_e32 v12, v12, v23
	v_lshlrev_b32_e32 v20, 16, v87
	v_and_b32_e32 v87, 0xffff0000, v87
	v_mul_f32_e32 v20, 0x3fb8aa3b, v20
	v_lshlrev_b32_e32 v21, 16, v88
	v_and_b32_e32 v88, 0xffff0000, v88
	v_mul_f32_e32 v21, 0x3fb8aa3b, v21
	v_lshlrev_b32_e32 v22, 16, v89
	v_and_b32_e32 v89, 0xffff0000, v89
	v_mul_f32_e32 v22, 0x3fb8aa3b, v22
	v_lshlrev_b32_e32 v23, 16, v90
	v_and_b32_e32 v90, 0xffff0000, v90
	v_mul_f32_e32 v23, 0x3fb8aa3b, v23
	v_exp_f32_e32 v20, v20
	v_exp_f32_e32 v21, v21
	v_exp_f32_e32 v22, v22
	v_exp_f32_e32 v23, v23
	s_nop 0
	v_fmac_f32_e32 v87, v86, v20
	v_mul_f32_e32 v12, v12, v20
	v_fmac_f32_e32 v88, v87, v21
	v_mul_f32_e32 v12, v12, v21
	v_fmac_f32_e32 v89, v88, v22
	v_mul_f32_e32 v12, v12, v22
	v_fmac_f32_e32 v90, v89, v23
	v_mul_f32_e32 v12, v12, v23
	v_lshlrev_b32_e32 v20, 16, v91
	v_and_b32_e32 v91, 0xffff0000, v91
	v_mul_f32_e32 v20, 0x3fb8aa3b, v20
	v_lshlrev_b32_e32 v21, 16, v92
	v_and_b32_e32 v92, 0xffff0000, v92
	v_mul_f32_e32 v21, 0x3fb8aa3b, v21
	v_lshlrev_b32_e32 v22, 16, v93
	v_and_b32_e32 v93, 0xffff0000, v93
	v_mul_f32_e32 v22, 0x3fb8aa3b, v22
	v_lshlrev_b32_e32 v23, 16, v94
	v_and_b32_e32 v94, 0xffff0000, v94
	v_mul_f32_e32 v23, 0x3fb8aa3b, v23
	v_exp_f32_e32 v20, v20
	v_exp_f32_e32 v21, v21
	v_exp_f32_e32 v22, v22
	v_exp_f32_e32 v23, v23
	s_nop 0
	v_fmac_f32_e32 v91, v90, v20
	v_mul_f32_e32 v12, v12, v20
	v_fmac_f32_e32 v92, v91, v21
	v_mul_f32_e32 v12, v12, v21
	v_fmac_f32_e32 v93, v92, v22
	v_mul_f32_e32 v12, v12, v22
	v_fmac_f32_e32 v94, v93, v23
	v_mul_f32_e32 v12, v12, v23
	s_waitcnt vmcnt(0)
	v_lshlrev_b32_e32 v20, 16, v95
	v_and_b32_e32 v95, 0xffff0000, v95
	v_mul_f32_e32 v20, 0x3fb8aa3b, v20
	v_lshlrev_b32_e32 v21, 16, v96
	v_and_b32_e32 v96, 0xffff0000, v96
	v_mul_f32_e32 v21, 0x3fb8aa3b, v21
	v_lshlrev_b32_e32 v22, 16, v97
	v_and_b32_e32 v97, 0xffff0000, v97
	v_mul_f32_e32 v22, 0x3fb8aa3b, v22
	v_lshlrev_b32_e32 v23, 16, v98
	v_and_b32_e32 v98, 0xffff0000, v98
	v_mul_f32_e32 v23, 0x3fb8aa3b, v23
	v_exp_f32_e32 v20, v20
	v_exp_f32_e32 v21, v21
	v_exp_f32_e32 v22, v22
	v_exp_f32_e32 v23, v23
	s_nop 0
	v_fmac_f32_e32 v95, v94, v20
	v_mul_f32_e32 v12, v12, v20
	v_fmac_f32_e32 v96, v95, v21
	v_mul_f32_e32 v12, v12, v21
	v_fmac_f32_e32 v97, v96, v22
	v_mul_f32_e32 v12, v12, v22
	v_fmac_f32_e32 v98, v97, v23
	v_mul_f32_e32 v12, v12, v23
	v_lshlrev_b32_e32 v20, 16, v99
	v_and_b32_e32 v99, 0xffff0000, v99
	v_mul_f32_e32 v20, 0x3fb8aa3b, v20
	v_lshlrev_b32_e32 v21, 16, v100
	v_and_b32_e32 v100, 0xffff0000, v100
	v_mul_f32_e32 v21, 0x3fb8aa3b, v21
	v_lshlrev_b32_e32 v22, 16, v101
	v_and_b32_e32 v101, 0xffff0000, v101
	v_mul_f32_e32 v22, 0x3fb8aa3b, v22
	v_lshlrev_b32_e32 v23, 16, v102
	v_and_b32_e32 v102, 0xffff0000, v102
	v_mul_f32_e32 v23, 0x3fb8aa3b, v23
	v_exp_f32_e32 v20, v20
	v_exp_f32_e32 v21, v21
	v_exp_f32_e32 v22, v22
	v_exp_f32_e32 v23, v23
	s_nop 0
	v_fmac_f32_e32 v99, v98, v20
	v_mul_f32_e32 v12, v12, v20
	v_fmac_f32_e32 v100, v99, v21
	v_mul_f32_e32 v12, v12, v21
	v_fmac_f32_e32 v101, v100, v22
	v_mul_f32_e32 v12, v12, v22
	v_fmac_f32_e32 v102, v101, v23
	v_mul_f32_e32 v12, v12, v23
	v_lshlrev_b32_e32 v20, 16, v103
	v_and_b32_e32 v103, 0xffff0000, v103
	v_mul_f32_e32 v20, 0x3fb8aa3b, v20
	v_lshlrev_b32_e32 v21, 16, v104
	v_and_b32_e32 v104, 0xffff0000, v104
	v_mul_f32_e32 v21, 0x3fb8aa3b, v21
	v_lshlrev_b32_e32 v22, 16, v105
	v_and_b32_e32 v105, 0xffff0000, v105
	v_mul_f32_e32 v22, 0x3fb8aa3b, v22
	v_lshlrev_b32_e32 v23, 16, v106
	v_and_b32_e32 v106, 0xffff0000, v106
	v_mul_f32_e32 v23, 0x3fb8aa3b, v23
	v_exp_f32_e32 v20, v20
	v_exp_f32_e32 v21, v21
	v_exp_f32_e32 v22, v22
	v_exp_f32_e32 v23, v23
	s_nop 0
	v_fmac_f32_e32 v103, v102, v20
	v_mul_f32_e32 v12, v12, v20
	v_fmac_f32_e32 v104, v103, v21
	v_mul_f32_e32 v12, v12, v21
	v_fmac_f32_e32 v105, v104, v22
	v_mul_f32_e32 v12, v12, v22
	v_fmac_f32_e32 v106, v105, v23
	v_mul_f32_e32 v12, v12, v23
	v_lshlrev_b32_e32 v20, 16, v107
	v_and_b32_e32 v107, 0xffff0000, v107
	v_mul_f32_e32 v20, 0x3fb8aa3b, v20
	v_lshlrev_b32_e32 v21, 16, v108
	v_and_b32_e32 v108, 0xffff0000, v108
	v_mul_f32_e32 v21, 0x3fb8aa3b, v21
	v_lshlrev_b32_e32 v22, 16, v109
	v_and_b32_e32 v109, 0xffff0000, v109
	v_mul_f32_e32 v22, 0x3fb8aa3b, v22
	v_lshlrev_b32_e32 v23, 16, v110
	v_and_b32_e32 v110, 0xffff0000, v110
	v_mul_f32_e32 v23, 0x3fb8aa3b, v23
	v_exp_f32_e32 v20, v20
	v_exp_f32_e32 v21, v21
	v_exp_f32_e32 v22, v22
	v_exp_f32_e32 v23, v23
	s_nop 0
	v_fmac_f32_e32 v107, v106, v20
	v_mul_f32_e32 v12, v12, v20
	v_fmac_f32_e32 v108, v107, v21
	v_mul_f32_e32 v12, v12, v21
	v_fmac_f32_e32 v109, v108, v22
	v_mul_f32_e32 v12, v12, v22
	v_fmac_f32_e32 v110, v109, v23
	v_mul_f32_e32 v12, v12, v23
	v_mov_b32_e32 v13, v110
	s_and_saveexec_b64 s[6:7], s[4:5]
	ds_write_b64 v19, v[12:13]
	s_or_b64 exec, exec, s[6:7]
	s_waitcnt lgkmcnt(0)
	s_barrier
	s_and_saveexec_b64 s[6:7], s[0:1]
	s_cbranch_execz .LBB0_381
	ds_read_b64 v[10:11], v19
	v_lshlrev_b64 v[8:9], 13, v[8:9]
	v_lshl_add_u64 v[8:9], s[70:71], 0, v[8:9]
	v_lshl_add_u64 v[6:7], v[6:7], 3, v[8:9]
	s_waitcnt lgkmcnt(0)
	v_mul_f32_e32 v13, v13, v10
	v_pk_mul_f32 v[14:15], v[12:13], v[10:11]
	v_pk_add_f32 v[10:11], v[12:13], v[10:11]
	s_nop 0
	v_mov_b32_e32 v15, v11
	global_store_dwordx2 v[6:7], v[14:15], off
	s_branch .LBB0_381
